# SwiGLU GEMM epilogue list-scheduled: chain temporaries renamed onto 4 idle VGPRs, 4 silu*up chains in flight, all 129 s_nop pads removed
# baseline (speedup 1.0000x reference)
.LBB0_140:
	v_mul_f32_e32 v249, 0xbfb8aa3b, v125
	v_mul_f32_e32 v250, 0xbfb8aa3b, v126
	v_exp_f32_e32 v249, v249
	v_exp_f32_e32 v250, v250
	v_mul_f32_e32 v251, 0xbfb8aa3b, v127
	v_exp_f32_e32 v251, v251
	v_add_f32_e32 v249, 1.0, v249
	v_add_f32_e32 v250, 1.0, v250
	v_rcp_f32_e32 v249, v249
	v_rcp_f32_e32 v250, v250
	v_add_f32_e32 v251, 1.0, v251
	v_rcp_f32_e32 v251, v251
	v_mul_f32_e32 v249, v125, v249
	v_mul_f32_e32 v250, v126, v250
	v_mul_f32_e32 v121, v121, v249
	v_mul_f32_e32 v122, v122, v250
	v_mul_f32_e32 v251, v127, v251
	v_mul_f32_e32 v123, v123, v251
	v_mul_f32_e32 v249, 0xbfb8aa3b, v117
	v_mul_f32_e32 v250, 0xbfb8aa3b, v118
	v_exp_f32_e32 v249, v249
	v_exp_f32_e32 v250, v250
	v_mul_f32_e32 v251, 0xbfb8aa3b, v119
	v_exp_f32_e32 v251, v251
	v_add_f32_e32 v249, 1.0, v249
	v_add_f32_e32 v250, 1.0, v250
	v_mul_f32_e32 v248, 0xbfb8aa3b, v124
	v_rcp_f32_e32 v249, v249
	v_rcp_f32_e32 v250, v250
	v_add_f32_e32 v251, 1.0, v251
	v_exp_f32_e32 v248, v248
	v_rcp_f32_e32 v251, v251
	v_mul_f32_e32 v249, v117, v249
	v_mul_f32_e32 v250, v118, v250
	v_add_f32_e32 v248, 1.0, v248
	v_mul_f32_e32 v113, v113, v249
	v_mul_f32_e32 v114, v114, v250
	v_mul_f32_e32 v251, v119, v251
	v_rcp_f32_e32 v248, v248
	v_mul_f32_e32 v115, v115, v251
	v_mul_f32_e32 v249, 0xbfb8aa3b, v109
	v_mul_f32_e32 v250, 0xbfb8aa3b, v110
	v_exp_f32_e32 v249, v249
	v_exp_f32_e32 v250, v250
	v_mul_f32_e32 v251, 0xbfb8aa3b, v111
	v_exp_f32_e32 v251, v251
	v_mul_f32_e32 v124, v124, v248
	v_mul_f32_e32 v248, 0xbfb8aa3b, v116
	v_add_f32_e32 v249, 1.0, v249
	v_add_f32_e32 v250, 1.0, v250
	v_exp_f32_e32 v248, v248
	v_rcp_f32_e32 v249, v249
	v_rcp_f32_e32 v250, v250
	v_add_f32_e32 v251, 1.0, v251
	v_rcp_f32_e32 v251, v251
	v_add_f32_e32 v248, 1.0, v248
	v_mul_f32_e32 v249, v109, v249
	v_mul_f32_e32 v250, v110, v250
	v_rcp_f32_e32 v248, v248
	v_mul_f32_e32 v105, v105, v249
	v_mul_f32_e32 v106, v106, v250
	v_mul_f32_e32 v251, v111, v251
	v_mul_f32_e32 v107, v107, v251
	v_mul_f32_e32 v249, 0xbfb8aa3b, v101
	v_mul_f32_e32 v250, 0xbfb8aa3b, v102
	v_exp_f32_e32 v249, v249
	v_exp_f32_e32 v250, v250
	v_mul_f32_e32 v251, 0xbfb8aa3b, v103
	v_mul_f32_e32 v116, v116, v248
	v_exp_f32_e32 v251, v251
	v_mul_f32_e32 v248, 0xbfb8aa3b, v108
	v_exp_f32_e32 v248, v248
	v_add_f32_e32 v249, 1.0, v249
	v_add_f32_e32 v250, 1.0, v250
	v_rcp_f32_e32 v249, v249
	v_rcp_f32_e32 v250, v250
	v_add_f32_e32 v251, 1.0, v251
	v_rcp_f32_e32 v251, v251
	v_add_f32_e32 v248, 1.0, v248
	v_rcp_f32_e32 v248, v248
	v_mul_f32_e32 v249, v101, v249
	v_mul_f32_e32 v250, v102, v250
	v_mul_f32_e32 v101, v97, v249
	v_mul_f32_e32 v102, v98, v250
	v_mul_f32_e32 v251, v103, v251
	v_mul_f32_e32 v99, v99, v251
	v_mul_f32_e32 v249, 0xbfb8aa3b, v93
	v_mul_f32_e32 v250, 0xbfb8aa3b, v94
	v_mul_f32_e32 v108, v108, v248
	v_exp_f32_e32 v249, v249
	v_exp_f32_e32 v250, v250
	v_mul_f32_e32 v251, 0xbfb8aa3b, v95
	v_mul_f32_e32 v248, 0xbfb8aa3b, v100
	v_exp_f32_e32 v251, v251
	v_exp_f32_e32 v248, v248
	v_add_f32_e32 v249, 1.0, v249
	v_add_f32_e32 v250, 1.0, v250
	v_rcp_f32_e32 v249, v249
	v_rcp_f32_e32 v250, v250
	v_add_f32_e32 v251, 1.0, v251
	v_add_f32_e32 v248, 1.0, v248
	v_rcp_f32_e32 v251, v251
	v_rcp_f32_e32 v248, v248
	v_mul_f32_e32 v249, v93, v249
	v_mul_f32_e32 v250, v94, v250
	v_mul_f32_e32 v89, v89, v249
	v_mul_f32_e32 v90, v90, v250
	v_mul_f32_e32 v251, v95, v251
	v_mul_f32_e32 v100, v100, v248
	v_mul_f32_e32 v91, v91, v251
	v_mul_f32_e32 v249, 0xbfb8aa3b, v85
	v_mul_f32_e32 v250, 0xbfb8aa3b, v86
	v_mul_f32_e32 v248, 0xbfb8aa3b, v92
	v_exp_f32_e32 v249, v249
	v_exp_f32_e32 v250, v250
	v_mul_f32_e32 v251, 0xbfb8aa3b, v87
	v_exp_f32_e32 v248, v248
	v_exp_f32_e32 v251, v251
	v_add_f32_e32 v249, 1.0, v249
	v_add_f32_e32 v250, 1.0, v250
	v_add_f32_e32 v248, 1.0, v248
	v_rcp_f32_e32 v249, v249
	v_rcp_f32_e32 v250, v250
	v_add_f32_e32 v251, 1.0, v251
	v_rcp_f32_e32 v248, v248
	v_rcp_f32_e32 v251, v251
	v_mul_f32_e32 v249, v85, v249
	v_mul_f32_e32 v250, v86, v250
	v_mul_f32_e32 v92, v92, v248
	v_mul_f32_e32 v85, v81, v249
	v_mul_f32_e32 v86, v82, v250
	v_mul_f32_e32 v251, v87, v251
	v_mul_f32_e32 v248, 0xbfb8aa3b, v84
	v_mul_f32_e32 v83, v83, v251
	v_mul_f32_e32 v249, 0xbfb8aa3b, v77
	v_mul_f32_e32 v250, 0xbfb8aa3b, v78
	v_exp_f32_e32 v248, v248
	v_exp_f32_e32 v249, v249
	v_exp_f32_e32 v250, v250
	v_mul_f32_e32 v251, 0xbfb8aa3b, v79
	v_exp_f32_e32 v251, v251
	v_add_f32_e32 v248, 1.0, v248
	v_add_f32_e32 v249, 1.0, v249
	v_add_f32_e32 v250, 1.0, v250
	v_rcp_f32_e32 v248, v248
	v_rcp_f32_e32 v249, v249
	v_rcp_f32_e32 v250, v250
	v_add_f32_e32 v251, 1.0, v251
	v_rcp_f32_e32 v251, v251
	v_mul_f32_e32 v84, v84, v248
	v_mul_f32_e32 v249, v77, v249
	v_mul_f32_e32 v250, v78, v250
	v_mul_f32_e32 v248, 0xbfb8aa3b, v76
	v_mul_f32_e32 v73, v73, v249
	v_mul_f32_e32 v74, v74, v250
	v_mul_f32_e32 v251, v79, v251
	v_exp_f32_e32 v248, v248
	v_mul_f32_e32 v75, v75, v251
	v_mul_f32_e32 v249, 0xbfb8aa3b, v69
	v_mul_f32_e32 v250, 0xbfb8aa3b, v70
	v_exp_f32_e32 v249, v249
	v_exp_f32_e32 v250, v250
	v_mul_f32_e32 v251, 0xbfb8aa3b, v71
	v_exp_f32_e32 v251, v251
	v_add_f32_e32 v248, 1.0, v248
	v_rcp_f32_e32 v248, v248
	v_add_f32_e32 v249, 1.0, v249
	v_add_f32_e32 v250, 1.0, v250
	v_rcp_f32_e32 v249, v249
	v_rcp_f32_e32 v250, v250
	v_add_f32_e32 v251, 1.0, v251
	v_rcp_f32_e32 v251, v251
	v_mul_f32_e32 v76, v76, v248
	v_mul_f32_e32 v248, 0xbfb8aa3b, v68
	v_mul_f32_e32 v249, v69, v249
	v_mul_f32_e32 v250, v70, v250
	v_exp_f32_e32 v248, v248
	v_mul_f32_e32 v69, v65, v249
	v_mul_f32_e32 v70, v66, v250
	v_mul_f32_e32 v251, v71, v251
	v_mul_f32_e32 v67, v67, v251
	v_mul_f32_e32 v249, 0xbfb8aa3b, v61
	v_mul_f32_e32 v250, 0xbfb8aa3b, v62
	v_exp_f32_e32 v249, v249
	v_exp_f32_e32 v250, v250
	v_mul_f32_e32 v251, 0xbfb8aa3b, v63
	v_add_f32_e32 v248, 1.0, v248
	v_exp_f32_e32 v251, v251
	v_rcp_f32_e32 v248, v248
	v_add_f32_e32 v249, 1.0, v249
	v_add_f32_e32 v250, 1.0, v250
	v_rcp_f32_e32 v249, v249
	v_rcp_f32_e32 v250, v250
	v_add_f32_e32 v251, 1.0, v251
	v_mul_f32_e32 v68, v68, v248
	v_rcp_f32_e32 v251, v251
	v_mul_f32_e32 v248, 0xbfb8aa3b, v60
	v_exp_f32_e32 v248, v248
	v_mul_f32_e32 v249, v61, v249
	v_mul_f32_e32 v250, v62, v250
	v_mul_f32_e32 v57, v57, v249
	v_mul_f32_e32 v58, v58, v250
	v_mul_f32_e32 v251, v63, v251
	v_mul_f32_e32 v59, v59, v251
	v_mul_f32_e32 v249, 0xbfb8aa3b, v53
	v_mul_f32_e32 v250, 0xbfb8aa3b, v54
	v_add_f32_e32 v248, 1.0, v248
	v_exp_f32_e32 v249, v249
	v_exp_f32_e32 v250, v250
	v_mul_f32_e32 v251, 0xbfb8aa3b, v55
	v_rcp_f32_e32 v248, v248
	v_exp_f32_e32 v251, v251
	v_add_f32_e32 v249, 1.0, v249
	v_add_f32_e32 v250, 1.0, v250
	v_mul_f32_e32 v60, v60, v248
	v_rcp_f32_e32 v249, v249
	v_rcp_f32_e32 v250, v250
	v_add_f32_e32 v251, 1.0, v251
	v_mul_f32_e32 v248, 0xbfb8aa3b, v52
	v_rcp_f32_e32 v251, v251
	v_exp_f32_e32 v248, v248
	v_mul_f32_e32 v249, v53, v249
	v_mul_f32_e32 v250, v54, v250
	v_mul_f32_e32 v53, v49, v249
	v_mul_f32_e32 v54, v50, v250
	v_mul_f32_e32 v251, v55, v251
	v_add_f32_e32 v248, 1.0, v248
	v_mul_f32_e32 v51, v51, v251
	v_mul_f32_e32 v249, 0xbfb8aa3b, v45
	v_mul_f32_e32 v250, 0xbfb8aa3b, v46
	v_rcp_f32_e32 v248, v248
	v_exp_f32_e32 v249, v249
	v_exp_f32_e32 v250, v250
	v_mul_f32_e32 v251, 0xbfb8aa3b, v47
	v_exp_f32_e32 v251, v251
	v_mul_f32_e32 v52, v52, v248
	v_add_f32_e32 v249, 1.0, v249
	v_add_f32_e32 v250, 1.0, v250
	v_mul_f32_e32 v248, 0xbfb8aa3b, v44
	v_rcp_f32_e32 v249, v249
	v_rcp_f32_e32 v250, v250
	v_add_f32_e32 v251, 1.0, v251
	v_exp_f32_e32 v248, v248
	v_rcp_f32_e32 v251, v251
	v_mul_f32_e32 v249, v45, v249
	v_mul_f32_e32 v250, v46, v250
	v_add_f32_e32 v248, 1.0, v248
	v_mul_f32_e32 v41, v41, v249
	v_mul_f32_e32 v42, v42, v250
	v_mul_f32_e32 v251, v47, v251
	v_rcp_f32_e32 v248, v248
	v_mul_f32_e32 v43, v43, v251
	v_mul_f32_e32 v249, 0xbfb8aa3b, v37
	v_mul_f32_e32 v250, 0xbfb8aa3b, v38
	v_exp_f32_e32 v249, v249
	v_exp_f32_e32 v250, v250
	v_mul_f32_e32 v251, 0xbfb8aa3b, v39
	v_exp_f32_e32 v251, v251
	v_mul_f32_e32 v44, v44, v248
	v_mul_f32_e32 v248, 0xbfb8aa3b, v36
	v_add_f32_e32 v249, 1.0, v249
	v_add_f32_e32 v250, 1.0, v250
	v_exp_f32_e32 v248, v248
	v_rcp_f32_e32 v249, v249
	v_rcp_f32_e32 v250, v250
	v_add_f32_e32 v251, 1.0, v251
	v_rcp_f32_e32 v251, v251
	v_add_f32_e32 v248, 1.0, v248
	v_mul_f32_e32 v249, v37, v249
	v_mul_f32_e32 v250, v38, v250
	v_rcp_f32_e32 v248, v248
	v_mul_f32_e32 v37, v33, v249
	v_mul_f32_e32 v38, v34, v250
	v_mul_f32_e32 v251, v39, v251
	v_mul_f32_e32 v35, v35, v251
	v_mul_f32_e32 v249, 0xbfb8aa3b, v29
	v_mul_f32_e32 v250, 0xbfb8aa3b, v30
	v_exp_f32_e32 v249, v249
	v_exp_f32_e32 v250, v250
	v_mul_f32_e32 v251, 0xbfb8aa3b, v31
	v_mul_f32_e32 v36, v36, v248
	v_exp_f32_e32 v251, v251
	v_mul_f32_e32 v248, 0xbfb8aa3b, v28
	v_exp_f32_e32 v248, v248
	v_add_f32_e32 v249, 1.0, v249
	v_add_f32_e32 v250, 1.0, v250
	v_rcp_f32_e32 v249, v249
	v_rcp_f32_e32 v250, v250
	v_add_f32_e32 v251, 1.0, v251
	v_rcp_f32_e32 v251, v251
	v_add_f32_e32 v248, 1.0, v248
	v_rcp_f32_e32 v248, v248
	v_mul_f32_e32 v249, v29, v249
	v_mul_f32_e32 v250, v30, v250
	v_mul_f32_e32 v25, v25, v249
	v_mul_f32_e32 v26, v26, v250
	v_mul_f32_e32 v251, v31, v251
	v_mul_f32_e32 v27, v27, v251
	v_mul_f32_e32 v249, 0xbfb8aa3b, v21
	v_mul_f32_e32 v250, 0xbfb8aa3b, v22
	v_mul_f32_e32 v28, v28, v248
	v_exp_f32_e32 v249, v249
	v_exp_f32_e32 v250, v250
	v_mul_f32_e32 v251, 0xbfb8aa3b, v23
	v_mul_f32_e32 v248, 0xbfb8aa3b, v20
	v_exp_f32_e32 v251, v251
	v_exp_f32_e32 v248, v248
	v_add_f32_e32 v249, 1.0, v249
	v_add_f32_e32 v250, 1.0, v250
	v_rcp_f32_e32 v249, v249
	v_rcp_f32_e32 v250, v250
	v_add_f32_e32 v251, 1.0, v251
	v_add_f32_e32 v248, 1.0, v248
	v_rcp_f32_e32 v251, v251
	v_rcp_f32_e32 v248, v248
	v_mul_f32_e32 v249, v21, v249
	v_mul_f32_e32 v250, v22, v250
	v_mul_f32_e32 v21, v17, v249
	v_mul_f32_e32 v22, v18, v250
	v_mul_f32_e32 v251, v23, v251
	v_mul_f32_e32 v20, v20, v248
	v_mul_f32_e32 v19, v19, v251
	v_mul_f32_e32 v249, 0xbfb8aa3b, v13
	v_mul_f32_e32 v250, 0xbfb8aa3b, v14
	v_mul_f32_e32 v248, 0xbfb8aa3b, v12
	v_exp_f32_e32 v249, v249
	v_exp_f32_e32 v250, v250
	v_mul_f32_e32 v251, 0xbfb8aa3b, v15
	v_exp_f32_e32 v248, v248
	v_exp_f32_e32 v251, v251
	v_add_f32_e32 v249, 1.0, v249
	v_add_f32_e32 v250, 1.0, v250
	v_add_f32_e32 v248, 1.0, v248
	v_rcp_f32_e32 v249, v249
	v_rcp_f32_e32 v250, v250
	v_add_f32_e32 v251, 1.0, v251
	v_mul_f32_e32 v112, v112, v116
	v_rcp_f32_e32 v248, v248
	v_rcp_f32_e32 v251, v251
	v_lshl_or_b32 v144, s84, 7, v140
	v_mul_f32_e32 v120, v120, v124
	v_cvt_pk_bf16_f32 v118, v112, v113
	v_lshl_add_u32 v142, s85, 8, v138
	v_ashrrev_i32_e32 v145, 31, v144
	v_mov_b64_e32 v[112:113], s[6:7]
	v_cvt_pk_bf16_f32 v116, v120, v121
	v_cvt_pk_bf16_f32 v119, v114, v115
	v_mul_f32_e32 v100, v96, v100
	v_mul_f32_e32 v249, v13, v249
	v_mul_f32_e32 v250, v14, v250
	v_mad_i64_i32 v[120:121], s[12:13], v142, s92, v[112:113]
	v_lshlrev_b64 v[114:115], 1, v[144:145]
	v_cvt_pk_bf16_f32 v98, v100, v101
	v_or_b32_e32 v103, 16, v142
	v_mul_f32_e32 v84, v80, v84
	v_mul_f32_e32 v12, v12, v248
	v_mul_f32_e32 v9, v9, v249
	v_mul_f32_e32 v10, v10, v250
	v_mul_f32_e32 v251, v15, v251
	v_cvt_pk_bf16_f32 v117, v122, v123
	v_lshl_add_u64 v[120:121], v[120:121], 0, v[114:115]
	v_mul_f32_e32 v104, v104, v108
	v_mad_i64_i32 v[100:101], s[12:13], v103, s92, v[112:113]
	v_cvt_pk_bf16_f32 v82, v84, v85
	v_or_b32_e32 v87, 32, v142
	v_mul_f32_e32 v68, v64, v68
	v_mul_f32_e32 v11, v11, v251
	v_mul_f32_e32 v248, 0xbfb8aa3b, v4
	v_mul_f32_e32 v249, 0xbfb8aa3b, v5
	v_mul_f32_e32 v250, 0xbfb8aa3b, v6
	global_store_dwordx4 v[120:121], v[116:119], off
	v_cvt_pk_bf16_f32 v97, v106, v107
	v_cvt_pk_bf16_f32 v96, v104, v105
	v_lshl_add_u64 v[100:101], v[100:101], 0, v[114:115]
	v_cvt_pk_bf16_f32 v99, v102, v99
	v_mul_f32_e32 v88, v88, v92
	v_mad_i64_i32 v[84:85], s[12:13], v87, s92, v[112:113]
	v_cvt_pk_bf16_f32 v66, v68, v69
	v_or_b32_e32 v71, 48, v142
	v_exp_f32_e32 v248, v248
	v_exp_f32_e32 v249, v249
	v_exp_f32_e32 v250, v250
	v_mul_f32_e32 v251, 0xbfb8aa3b, v7
	global_store_dwordx4 v[100:101], v[96:99], off
	v_cvt_pk_bf16_f32 v81, v90, v91
	v_cvt_pk_bf16_f32 v80, v88, v89
	v_lshl_add_u64 v[84:85], v[84:85], 0, v[114:115]
	v_cvt_pk_bf16_f32 v83, v86, v83
	v_mul_f32_e32 v72, v72, v76
	v_mad_i64_i32 v[68:69], s[12:13], v71, s92, v[112:113]
	v_exp_f32_e32 v251, v251
	global_store_dwordx4 v[84:85], v[80:83], off
	v_cvt_pk_bf16_f32 v65, v74, v75
	v_lshl_add_u64 v[68:69], v[68:69], 0, v[114:115]
	v_cvt_pk_bf16_f32 v64, v72, v73
	v_cvt_pk_bf16_f32 v67, v70, v67
	global_store_dwordx4 v[68:69], v[64:67], off
	v_add_f32_e32 v248, 1.0, v248
	v_add_f32_e32 v249, 1.0, v249
	v_add_f32_e32 v250, 1.0, v250
	v_rcp_f32_e32 v248, v248
	v_rcp_f32_e32 v249, v249
	v_rcp_f32_e32 v250, v250
	v_add_f32_e32 v251, 1.0, v251
	v_mul_f32_e32 v52, v48, v52
	v_rcp_f32_e32 v251, v251
	v_add_u32_e32 v64, 0x80, v142
	v_cvt_pk_bf16_f32 v50, v52, v53
	v_mul_f32_e32 v36, v32, v36
	v_mul_f32_e32 v56, v56, v60
	v_mad_i64_i32 v[52:53], s[12:13], v64, s92, v[112:113]
	v_cvt_pk_bf16_f32 v34, v36, v37
	v_add_u32_e32 v39, 0x90, v142
	v_mul_f32_e32 v20, v16, v20
	v_mul_f32_e32 v4, v4, v248
	v_mul_f32_e32 v249, v5, v249
	v_mul_f32_e32 v250, v6, v250
	v_cvt_pk_bf16_f32 v49, v58, v59
	v_lshl_add_u64 v[52:53], v[52:53], 0, v[114:115]
	v_cvt_pk_bf16_f32 v48, v56, v57
	v_cvt_pk_bf16_f32 v51, v54, v51
	v_mul_f32_e32 v40, v40, v44
	v_mad_i64_i32 v[36:37], s[12:13], v39, s92, v[112:113]
	v_cvt_pk_bf16_f32 v18, v20, v21
	v_add_u32_e32 v23, 0xa0, v142
	v_mul_f32_e32 v4, v0, v4
	v_mul_f32_e32 v5, v1, v249
	v_mul_f32_e32 v6, v2, v250
	v_mul_f32_e32 v251, v7, v251
	global_store_dwordx4 v[52:53], v[48:51], off
	v_cvt_pk_bf16_f32 v33, v42, v43
	v_cvt_pk_bf16_f32 v32, v40, v41
	v_lshl_add_u64 v[36:37], v[36:37], 0, v[114:115]
	v_cvt_pk_bf16_f32 v35, v38, v35
	v_mul_f32_e32 v24, v24, v28
	v_mad_i64_i32 v[20:21], s[12:13], v23, s92, v[112:113]
	v_cvt_pk_bf16_f32 v2, v4, v5
	v_add_u32_e32 v7, 0xb0, v142
	global_store_dwordx4 v[36:37], v[32:35], off
	v_cvt_pk_bf16_f32 v17, v26, v27
	v_cvt_pk_bf16_f32 v16, v24, v25
	v_lshl_add_u64 v[20:21], v[20:21], 0, v[114:115]
	v_cvt_pk_bf16_f32 v19, v22, v19
	v_mul_f32_e32 v8, v8, v12
	v_mad_i64_i32 v[4:5], s[12:13], v7, s92, v[112:113]
	v_mul_f32_e32 v3, v3, v251
	global_store_dwordx4 v[20:21], v[16:19], off
	v_cvt_pk_bf16_f32 v1, v10, v11
	v_lshl_add_u64 v[4:5], v[4:5], 0, v[114:115]
	v_cvt_pk_bf16_f32 v0, v8, v9
	v_cvt_pk_bf16_f32 v3, v6, v3
	s_mov_b64 s[28:29], -1
	s_and_b64 vcc, exec, s[40:41]
	global_store_dwordx4 v[4:5], v[0:3], off
	s_cbranch_vccnz .LBB0_130
	s_andn2_b64 vcc, exec, s[46:47]
	s_cbranch_vccnz .LBB0_129
	s_barrier
	s_branch .LBB0_129
